# dwconv interior fast body: next unit's halo rows streamed in a full iteration ahead (row r reloaded right after its last use)
# baseline (speedup 1.0000x reference)
.Ldw_fast:
	s_mov_b32 s96, s70
	s_mov_b32 s97, s84
	s_add_i32 s3, s94, s70
	v_readlane_b32 s0, v254, 23
	v_readlane_b32 s7, v255, 22
	s_sub_i32 s4, s3, 1
	s_cmpk_lt_u32 s4, 0x3fe
	s_cselect_b32 s6, 1, 0
	s_sub_i32 s4, s3, 0x401
	s_cmp_lt_u32 s4, 14
	s_cselect_b32 s4, 1, 0
	s_or_b32 s6, s6, s4
	s_cmp_lt_i32 s3, s0
	s_cselect_b32 s6, s6, 0
	v_writelane_b32 v255, s6, 22
	s_cmp_lg_u32 s7, 0
	s_cbranch_scc1 .Ldw_have
	s_add_i32 s4, s2, -15
	s_ashr_i32 s5, s4, 31
	s_lshl_b64 s[4:5], s[4:5], 11
	v_lshl_add_u64 v[174:175], v[114:115], 0, s[4:5]
	global_load_dword v206, v[174:175], off
	global_load_dword v207, v[174:175], off offset:2048
	s_add_u32 s4, s4, 0x1000
	s_addc_u32 s5, s5, 0
	v_lshl_add_u64 v[176:177], v[114:115], 0, s[4:5]
	global_load_dword v208, v[176:177], off
	global_load_dword v209, v[176:177], off offset:2048
	s_add_u32 s4, s4, 0x1000
	s_addc_u32 s5, s5, 0
	v_lshl_add_u64 v[174:175], v[114:115], 0, s[4:5]
	global_load_dword v210, v[174:175], off
	global_load_dword v211, v[174:175], off offset:2048
	s_add_u32 s4, s4, 0x1000
	s_addc_u32 s5, s5, 0
	v_lshl_add_u64 v[176:177], v[114:115], 0, s[4:5]
	global_load_dword v212, v[176:177], off
	global_load_dword v213, v[176:177], off offset:2048
	s_add_u32 s4, s4, 0x1000
	s_addc_u32 s5, s5, 0
	v_lshl_add_u64 v[174:175], v[114:115], 0, s[4:5]
	global_load_dword v214, v[174:175], off
	global_load_dword v215, v[174:175], off offset:2048
	s_add_u32 s4, s4, 0x1000
	s_addc_u32 s5, s5, 0
	v_lshl_add_u64 v[176:177], v[114:115], 0, s[4:5]
	global_load_dword v216, v[176:177], off
	global_load_dword v217, v[176:177], off offset:2048
	s_add_u32 s4, s4, 0x1000
	s_addc_u32 s5, s5, 0
	v_lshl_add_u64 v[174:175], v[114:115], 0, s[4:5]
	global_load_dword v218, v[174:175], off
	global_load_dword v219, v[174:175], off offset:2048
	s_add_u32 s4, s4, 0x1000
	s_addc_u32 s5, s5, 0
	v_lshl_add_u64 v[176:177], v[114:115], 0, s[4:5]
	global_load_dword v220, v[176:177], off
	global_load_dword v221, v[176:177], off offset:2048
	s_add_u32 s4, s4, 0x1000
	s_addc_u32 s5, s5, 0
	v_lshl_add_u64 v[174:175], v[114:115], 0, s[4:5]
	global_load_dword v222, v[174:175], off
	global_load_dword v223, v[174:175], off offset:2048
	s_add_u32 s4, s4, 0x1000
	s_addc_u32 s5, s5, 0
	v_lshl_add_u64 v[176:177], v[114:115], 0, s[4:5]
	global_load_dword v224, v[176:177], off
	global_load_dword v225, v[176:177], off offset:2048
	s_add_u32 s4, s4, 0x1000
	s_addc_u32 s5, s5, 0
	v_lshl_add_u64 v[174:175], v[114:115], 0, s[4:5]
	global_load_dword v226, v[174:175], off
	global_load_dword v227, v[174:175], off offset:2048
	s_add_u32 s4, s4, 0x1000
	s_addc_u32 s5, s5, 0
	v_lshl_add_u64 v[176:177], v[114:115], 0, s[4:5]
	global_load_dword v228, v[176:177], off
	global_load_dword v229, v[176:177], off offset:2048
	s_add_u32 s4, s4, 0x1000
	s_addc_u32 s5, s5, 0
	v_lshl_add_u64 v[174:175], v[114:115], 0, s[4:5]
	global_load_dword v230, v[174:175], off
	global_load_dword v231, v[174:175], off offset:2048
	s_add_u32 s4, s4, 0x1000
	s_addc_u32 s5, s5, 0
	v_lshl_add_u64 v[176:177], v[114:115], 0, s[4:5]
	global_load_dword v232, v[176:177], off
	global_load_dword v233, v[176:177], off offset:2048
	s_add_u32 s4, s4, 0x1000
	s_addc_u32 s5, s5, 0
	v_lshl_add_u64 v[174:175], v[114:115], 0, s[4:5]
	global_load_dword v234, v[174:175], off
	global_load_dword v235, v[174:175], off offset:2048
	s_add_u32 s4, s4, 0x1000
	s_addc_u32 s5, s5, 0
	v_lshl_add_u64 v[176:177], v[114:115], 0, s[4:5]
	global_load_dword v236, v[176:177], off
	global_load_dword v237, v[176:177], off offset:2048
	s_add_u32 s4, s4, 0x1000
	s_addc_u32 s5, s5, 0
	v_lshl_add_u64 v[174:175], v[114:115], 0, s[4:5]
	global_load_dword v238, v[174:175], off
	global_load_dword v239, v[174:175], off offset:2048
	s_add_u32 s4, s4, 0x1000
	s_addc_u32 s5, s5, 0
	v_lshl_add_u64 v[176:177], v[114:115], 0, s[4:5]
	global_load_dword v240, v[176:177], off
	global_load_dword v241, v[176:177], off offset:2048
	s_add_u32 s4, s4, 0x1000
	s_addc_u32 s5, s5, 0
	v_lshl_add_u64 v[174:175], v[114:115], 0, s[4:5]
	global_load_dword v242, v[174:175], off
	global_load_dword v243, v[174:175], off offset:2048
	s_add_u32 s4, s4, 0x1000
	s_addc_u32 s5, s5, 0
	v_lshl_add_u64 v[176:177], v[114:115], 0, s[4:5]
	global_load_dword v244, v[176:177], off
	global_load_dword v245, v[176:177], off offset:2048
	s_add_u32 s4, s4, 0x1000
	s_addc_u32 s5, s5, 0
	v_lshl_add_u64 v[174:175], v[114:115], 0, s[4:5]
	global_load_dword v246, v[174:175], off
	global_load_dword v247, v[174:175], off offset:2048
	s_add_u32 s4, s4, 0x1000
	s_addc_u32 s5, s5, 0
	v_lshl_add_u64 v[176:177], v[114:115], 0, s[4:5]
	global_load_dword v248, v[176:177], off
	global_load_dword v249, v[176:177], off offset:2048
	s_add_u32 s4, s4, 0x1000
	s_addc_u32 s5, s5, 0
	v_lshl_add_u64 v[174:175], v[114:115], 0, s[4:5]
	global_load_dword v250, v[174:175], off
	global_load_dword v251, v[174:175], off offset:2048
.Ldw_have:
	s_cmp_lg_u32 s6, 0
	s_cselect_b32 s4, s84, 0
	s_add_i32 s4, s4, s2
	s_add_i32 s4, s4, -15
	s_ashr_i32 s5, s4, 31
	s_lshl_b64 s[4:5], s[4:5], 11
	s_waitcnt vmcnt(45)
	v_and_b32_e32 v143, 0xffff0000, v206
	s_waitcnt vmcnt(44)
	v_lshlrev_b32_e32 v144, 16, v207
	v_and_b32_e32 v145, 0xffff0000, v207
	s_waitcnt vmcnt(43)
	v_lshlrev_b32_e32 v146, 16, v208
	v_and_b32_e32 v147, 0xffff0000, v208
	s_waitcnt vmcnt(42)
	v_lshlrev_b32_e32 v148, 16, v209
	v_and_b32_e32 v149, 0xffff0000, v209
	s_waitcnt vmcnt(41)
	v_lshlrev_b32_e32 v152, 16, v210
	v_and_b32_e32 v153, 0xffff0000, v210
	s_waitcnt vmcnt(40)
	v_lshlrev_b32_e32 v154, 16, v211
	v_and_b32_e32 v155, 0xffff0000, v211
	s_waitcnt vmcnt(39)
	v_lshlrev_b32_e32 v156, 16, v212
	v_lshlrev_b32_e32 v142, 16, v206
	v_lshl_add_u64 v[174:175], v[114:115], 0, s[4:5]
	global_load_dword v206, v[174:175], off
	global_load_dword v207, v[174:175], off offset:2048
	s_add_u32 s4, s4, 0x1000
	s_addc_u32 s5, s5, 0
	v_lshl_add_u64 v[176:177], v[114:115], 0, s[4:5]
	global_load_dword v208, v[176:177], off
	global_load_dword v209, v[176:177], off offset:2048
	s_add_u32 s4, s4, 0x1000
	s_addc_u32 s5, s5, 0
	v_lshl_add_u64 v[174:175], v[114:115], 0, s[4:5]
	global_load_dword v210, v[174:175], off
	global_load_dword v211, v[174:175], off offset:2048
	s_add_u32 s4, s4, 0x1000
	s_addc_u32 s5, s5, 0
	v_and_b32_e32 v157, 0xffff0000, v212
	v_lshl_add_u64 v[176:177], v[114:115], 0, s[4:5]
	global_load_dword v212, v[176:177], off
	s_waitcnt vmcnt(45)
	v_pk_fma_f32 v[142:143], v[54:55], v[142:143], v[112:113]
	v_lshlrev_b32_e32 v158, 16, v213
	v_pk_fma_f32 v[142:143], v[56:57], v[144:145], v[142:143]
	v_pk_fma_f32 v[144:145], v[54:55], v[144:145], v[112:113]
	v_and_b32_e32 v159, 0xffff0000, v213
	global_load_dword v213, v[176:177], off offset:2048
	s_add_u32 s4, s4, 0x1000
	s_addc_u32 s5, s5, 0
	s_waitcnt vmcnt(45)
	v_pk_fma_f32 v[142:143], v[58:59], v[146:147], v[142:143]
	v_pk_fma_f32 v[144:145], v[56:57], v[146:147], v[144:145]
	v_pk_fma_f32 v[146:147], v[54:55], v[146:147], v[112:113]
	v_lshlrev_b32_e32 v160, 16, v214
	v_pk_fma_f32 v[142:143], v[50:51], v[148:149], v[142:143]
	v_pk_fma_f32 v[144:145], v[58:59], v[148:149], v[144:145]
	v_pk_fma_f32 v[146:147], v[56:57], v[148:149], v[146:147]
	v_pk_fma_f32 v[148:149], v[54:55], v[148:149], v[112:113]
	v_and_b32_e32 v161, 0xffff0000, v214
	v_lshl_add_u64 v[174:175], v[114:115], 0, s[4:5]
	global_load_dword v214, v[174:175], off
	s_waitcnt vmcnt(45)
	v_pk_fma_f32 v[142:143], v[52:53], v[152:153], v[142:143]
	v_pk_fma_f32 v[144:145], v[50:51], v[152:153], v[144:145]
	v_pk_fma_f32 v[146:147], v[58:59], v[152:153], v[146:147]
	v_pk_fma_f32 v[148:149], v[56:57], v[152:153], v[148:149]
	v_pk_fma_f32 v[152:153], v[54:55], v[152:153], v[112:113]
	v_lshlrev_b32_e32 v162, 16, v215
	v_pk_fma_f32 v[142:143], v[60:61], v[154:155], v[142:143]
	v_pk_fma_f32 v[144:145], v[52:53], v[154:155], v[144:145]
	v_pk_fma_f32 v[146:147], v[50:51], v[154:155], v[146:147]
	v_pk_fma_f32 v[148:149], v[58:59], v[154:155], v[148:149]
	v_pk_fma_f32 v[152:153], v[56:57], v[154:155], v[152:153]
	v_pk_fma_f32 v[154:155], v[54:55], v[154:155], v[112:113]
	v_and_b32_e32 v163, 0xffff0000, v215
	global_load_dword v215, v[174:175], off offset:2048
	s_add_u32 s4, s4, 0x1000
	s_addc_u32 s5, s5, 0
	s_waitcnt vmcnt(45)
	v_pk_fma_f32 v[142:143], v[62:63], v[156:157], v[142:143]
	v_pk_fma_f32 v[144:145], v[60:61], v[156:157], v[144:145]
	v_pk_fma_f32 v[146:147], v[52:53], v[156:157], v[146:147]
	v_pk_fma_f32 v[148:149], v[50:51], v[156:157], v[148:149]
	v_pk_fma_f32 v[152:153], v[58:59], v[156:157], v[152:153]
	v_pk_fma_f32 v[154:155], v[56:57], v[156:157], v[154:155]
	v_pk_fma_f32 v[156:157], v[54:55], v[156:157], v[112:113]
	v_lshlrev_b32_e32 v164, 16, v216
	v_pk_fma_f32 v[142:143], v[64:65], v[158:159], v[142:143]
	v_pk_fma_f32 v[144:145], v[62:63], v[158:159], v[144:145]
	v_pk_fma_f32 v[146:147], v[60:61], v[158:159], v[146:147]
	v_pk_fma_f32 v[148:149], v[52:53], v[158:159], v[148:149]
	v_pk_fma_f32 v[152:153], v[50:51], v[158:159], v[152:153]
	v_pk_fma_f32 v[154:155], v[58:59], v[158:159], v[154:155]
	v_pk_fma_f32 v[156:157], v[56:57], v[158:159], v[156:157]
	v_pk_fma_f32 v[158:159], v[54:55], v[158:159], v[112:113]
	v_and_b32_e32 v165, 0xffff0000, v216
	v_lshl_add_u64 v[176:177], v[114:115], 0, s[4:5]
	global_load_dword v216, v[176:177], off
	s_waitcnt vmcnt(45)
	v_pk_fma_f32 v[142:143], v[66:67], v[160:161], v[142:143]
	v_pk_fma_f32 v[144:145], v[64:65], v[160:161], v[144:145]
	v_pk_fma_f32 v[146:147], v[62:63], v[160:161], v[146:147]
	v_pk_fma_f32 v[148:149], v[60:61], v[160:161], v[148:149]
	v_pk_fma_f32 v[152:153], v[52:53], v[160:161], v[152:153]
	v_pk_fma_f32 v[154:155], v[50:51], v[160:161], v[154:155]
	v_pk_fma_f32 v[156:157], v[58:59], v[160:161], v[156:157]
	v_pk_fma_f32 v[158:159], v[56:57], v[160:161], v[158:159]
	v_pk_fma_f32 v[160:161], v[54:55], v[160:161], v[112:113]
	v_lshlrev_b32_e32 v134, 16, v217
	v_pk_fma_f32 v[142:143], v[68:69], v[162:163], v[142:143]
	v_pk_fma_f32 v[144:145], v[66:67], v[162:163], v[144:145]
	v_pk_fma_f32 v[146:147], v[64:65], v[162:163], v[146:147]
	v_pk_fma_f32 v[148:149], v[62:63], v[162:163], v[148:149]
	v_pk_fma_f32 v[152:153], v[60:61], v[162:163], v[152:153]
	v_pk_fma_f32 v[154:155], v[52:53], v[162:163], v[154:155]
	v_pk_fma_f32 v[156:157], v[50:51], v[162:163], v[156:157]
	v_pk_fma_f32 v[158:159], v[58:59], v[162:163], v[158:159]
	v_pk_fma_f32 v[160:161], v[56:57], v[162:163], v[160:161]
	v_pk_fma_f32 v[162:163], v[54:55], v[162:163], v[112:113]
	v_and_b32_e32 v135, 0xffff0000, v217
	global_load_dword v217, v[176:177], off offset:2048
	s_add_u32 s4, s4, 0x1000
	s_addc_u32 s5, s5, 0
	s_waitcnt vmcnt(45)
	v_pk_fma_f32 v[142:143], v[70:71], v[164:165], v[142:143]
	v_pk_fma_f32 v[144:145], v[68:69], v[164:165], v[144:145]
	v_pk_fma_f32 v[146:147], v[66:67], v[164:165], v[146:147]
	v_pk_fma_f32 v[148:149], v[64:65], v[164:165], v[148:149]
	v_pk_fma_f32 v[152:153], v[62:63], v[164:165], v[152:153]
	v_pk_fma_f32 v[154:155], v[60:61], v[164:165], v[154:155]
	v_pk_fma_f32 v[156:157], v[52:53], v[164:165], v[156:157]
	v_pk_fma_f32 v[158:159], v[50:51], v[164:165], v[158:159]
	v_pk_fma_f32 v[160:161], v[58:59], v[164:165], v[160:161]
	v_pk_fma_f32 v[162:163], v[56:57], v[164:165], v[162:163]
	v_pk_fma_f32 v[164:165], v[54:55], v[164:165], v[112:113]
	v_lshlrev_b32_e32 v166, 16, v218
	v_pk_fma_f32 v[142:143], v[72:73], v[134:135], v[142:143]
	v_pk_fma_f32 v[144:145], v[70:71], v[134:135], v[144:145]
	v_pk_fma_f32 v[146:147], v[68:69], v[134:135], v[146:147]
	v_pk_fma_f32 v[148:149], v[66:67], v[134:135], v[148:149]
	v_pk_fma_f32 v[152:153], v[64:65], v[134:135], v[152:153]
	v_pk_fma_f32 v[154:155], v[62:63], v[134:135], v[154:155]
	v_pk_fma_f32 v[156:157], v[60:61], v[134:135], v[156:157]
	v_pk_fma_f32 v[158:159], v[52:53], v[134:135], v[158:159]
	v_pk_fma_f32 v[160:161], v[50:51], v[134:135], v[160:161]
	v_pk_fma_f32 v[162:163], v[58:59], v[134:135], v[162:163]
	v_pk_fma_f32 v[164:165], v[56:57], v[134:135], v[164:165]
	v_pk_fma_f32 v[134:135], v[54:55], v[134:135], v[112:113]
	v_and_b32_e32 v167, 0xffff0000, v218
	v_lshl_add_u64 v[174:175], v[114:115], 0, s[4:5]
	global_load_dword v218, v[174:175], off
	s_waitcnt vmcnt(45)
	v_pk_fma_f32 v[136:137], v[74:75], v[166:167], v[142:143]
	v_pk_fma_f32 v[142:143], v[72:73], v[166:167], v[144:145]
	v_pk_fma_f32 v[144:145], v[70:71], v[166:167], v[146:147]
	v_pk_fma_f32 v[146:147], v[68:69], v[166:167], v[148:149]
	v_pk_fma_f32 v[148:149], v[66:67], v[166:167], v[152:153]
	v_pk_fma_f32 v[152:153], v[64:65], v[166:167], v[154:155]
	v_pk_fma_f32 v[154:155], v[62:63], v[166:167], v[156:157]
	v_pk_fma_f32 v[156:157], v[60:61], v[166:167], v[158:159]
	v_pk_fma_f32 v[158:159], v[52:53], v[166:167], v[160:161]
	v_pk_fma_f32 v[160:161], v[50:51], v[166:167], v[162:163]
	v_pk_fma_f32 v[162:163], v[58:59], v[166:167], v[164:165]
	v_pk_fma_f32 v[134:135], v[56:57], v[166:167], v[134:135]
	v_pk_fma_f32 v[164:165], v[54:55], v[166:167], v[112:113]
	v_lshlrev_b32_e32 v166, 16, v219
	v_and_b32_e32 v167, 0xffff0000, v219
	global_load_dword v219, v[174:175], off offset:2048
	s_add_u32 s4, s4, 0x1000
	s_addc_u32 s5, s5, 0
	s_waitcnt vmcnt(45)
	v_lshlrev_b32_e32 v168, 16, v220
	v_and_b32_e32 v169, 0xffff0000, v220
	v_lshl_add_u64 v[176:177], v[114:115], 0, s[4:5]
	global_load_dword v220, v[176:177], off
	s_waitcnt vmcnt(45)
	v_lshlrev_b32_e32 v170, 16, v221
	v_pk_fma_f32 v[136:137], v[76:77], v[166:167], v[136:137]
	v_pk_fma_f32 v[142:143], v[74:75], v[166:167], v[142:143]
	v_pk_fma_f32 v[144:145], v[72:73], v[166:167], v[144:145]
	v_pk_fma_f32 v[146:147], v[70:71], v[166:167], v[146:147]
	v_pk_fma_f32 v[148:149], v[68:69], v[166:167], v[148:149]
	v_pk_fma_f32 v[152:153], v[66:67], v[166:167], v[152:153]
	v_pk_fma_f32 v[154:155], v[64:65], v[166:167], v[154:155]
	v_pk_fma_f32 v[156:157], v[62:63], v[166:167], v[156:157]
	v_pk_fma_f32 v[158:159], v[60:61], v[166:167], v[158:159]
	v_pk_fma_f32 v[160:161], v[52:53], v[166:167], v[160:161]
	v_pk_fma_f32 v[162:163], v[50:51], v[166:167], v[162:163]
	v_pk_fma_f32 v[134:135], v[58:59], v[166:167], v[134:135]
	v_pk_fma_f32 v[164:165], v[56:57], v[166:167], v[164:165]
	v_pk_fma_f32 v[166:167], v[54:55], v[166:167], v[112:113]
	v_and_b32_e32 v171, 0xffff0000, v221
	global_load_dword v221, v[176:177], off offset:2048
	s_add_u32 s4, s4, 0x1000
	s_addc_u32 s5, s5, 0
	s_waitcnt vmcnt(45)
	v_pk_fma_f32 v[136:137], v[78:79], v[168:169], v[136:137]
	v_pk_fma_f32 v[142:143], v[76:77], v[168:169], v[142:143]
	v_pk_fma_f32 v[144:145], v[74:75], v[168:169], v[144:145]
	v_pk_fma_f32 v[146:147], v[72:73], v[168:169], v[146:147]
	v_pk_fma_f32 v[148:149], v[70:71], v[168:169], v[148:149]
	v_pk_fma_f32 v[152:153], v[68:69], v[168:169], v[152:153]
	v_pk_fma_f32 v[154:155], v[66:67], v[168:169], v[154:155]
	v_pk_fma_f32 v[156:157], v[64:65], v[168:169], v[156:157]
	v_pk_fma_f32 v[158:159], v[62:63], v[168:169], v[158:159]
	v_pk_fma_f32 v[160:161], v[60:61], v[168:169], v[160:161]
	v_pk_fma_f32 v[162:163], v[52:53], v[168:169], v[162:163]
	v_pk_fma_f32 v[134:135], v[50:51], v[168:169], v[134:135]
	v_pk_fma_f32 v[164:165], v[58:59], v[168:169], v[164:165]
	v_pk_fma_f32 v[166:167], v[56:57], v[168:169], v[166:167]
	v_pk_fma_f32 v[168:169], v[54:55], v[168:169], v[112:113]
	v_lshlrev_b32_e32 v172, 16, v222
	v_pk_fma_f32 v[136:137], v[80:81], v[170:171], v[136:137]
	v_pk_fma_f32 v[142:143], v[78:79], v[170:171], v[142:143]
	v_pk_fma_f32 v[144:145], v[76:77], v[170:171], v[144:145]
	v_pk_fma_f32 v[146:147], v[74:75], v[170:171], v[146:147]
	v_pk_fma_f32 v[148:149], v[72:73], v[170:171], v[148:149]
	v_pk_fma_f32 v[152:153], v[70:71], v[170:171], v[152:153]
	v_pk_fma_f32 v[154:155], v[68:69], v[170:171], v[154:155]
	v_pk_fma_f32 v[156:157], v[66:67], v[170:171], v[156:157]
	v_pk_fma_f32 v[158:159], v[64:65], v[170:171], v[158:159]
	v_pk_fma_f32 v[160:161], v[62:63], v[170:171], v[160:161]
	v_pk_fma_f32 v[162:163], v[60:61], v[170:171], v[162:163]
	v_pk_fma_f32 v[134:135], v[52:53], v[170:171], v[134:135]
	v_pk_fma_f32 v[164:165], v[50:51], v[170:171], v[164:165]
	v_pk_fma_f32 v[166:167], v[58:59], v[170:171], v[166:167]
	v_pk_fma_f32 v[168:169], v[56:57], v[170:171], v[168:169]
	v_pk_fma_f32 v[170:171], v[54:55], v[170:171], v[112:113]
	v_and_b32_e32 v173, 0xffff0000, v222
	v_lshl_add_u64 v[174:175], v[114:115], 0, s[4:5]
	global_load_dword v222, v[174:175], off
	s_waitcnt vmcnt(45)
	v_pk_fma_f32 v[48:49], v[82:83], v[172:173], v[136:137]
	v_pk_fma_f32 v[136:137], v[80:81], v[172:173], v[142:143]
	v_pk_fma_f32 v[142:143], v[78:79], v[172:173], v[144:145]
	v_pk_fma_f32 v[144:145], v[76:77], v[172:173], v[146:147]
	v_pk_fma_f32 v[146:147], v[74:75], v[172:173], v[148:149]
	v_pk_fma_f32 v[148:149], v[72:73], v[172:173], v[152:153]
	v_pk_fma_f32 v[152:153], v[70:71], v[172:173], v[154:155]
	v_pk_fma_f32 v[154:155], v[68:69], v[172:173], v[156:157]
	v_pk_fma_f32 v[156:157], v[66:67], v[172:173], v[158:159]
	v_pk_fma_f32 v[158:159], v[64:65], v[172:173], v[160:161]
	v_pk_fma_f32 v[160:161], v[62:63], v[172:173], v[162:163]
	v_pk_fma_f32 v[162:163], v[52:53], v[172:173], v[164:165]
	v_pk_fma_f32 v[164:165], v[50:51], v[172:173], v[166:167]
	v_pk_fma_f32 v[166:167], v[58:59], v[172:173], v[168:169]
	v_pk_fma_f32 v[168:169], v[56:57], v[172:173], v[170:171]
	v_lshlrev_b32_e32 v170, 16, v223
	v_and_b32_e32 v171, 0xffff0000, v223
	global_load_dword v223, v[174:175], off offset:2048
	s_add_u32 s4, s4, 0x1000
	s_addc_u32 s5, s5, 0
	s_waitcnt vmcnt(45)
	v_pk_fma_f32 v[134:135], v[60:61], v[172:173], v[134:135]
	v_pk_fma_f32 v[46:47], v[84:85], v[170:171], v[48:49]
	v_pk_fma_f32 v[48:49], v[82:83], v[170:171], v[136:137]
	v_pk_fma_f32 v[136:137], v[80:81], v[170:171], v[142:143]
	v_pk_fma_f32 v[142:143], v[78:79], v[170:171], v[144:145]
	v_pk_fma_f32 v[144:145], v[76:77], v[170:171], v[146:147]
	v_pk_fma_f32 v[146:147], v[74:75], v[170:171], v[148:149]
	v_pk_fma_f32 v[148:149], v[72:73], v[170:171], v[152:153]
	v_pk_fma_f32 v[152:153], v[70:71], v[170:171], v[154:155]
	v_pk_fma_f32 v[154:155], v[68:69], v[170:171], v[156:157]
	v_pk_fma_f32 v[156:157], v[66:67], v[170:171], v[158:159]
	v_pk_fma_f32 v[158:159], v[64:65], v[170:171], v[160:161]
	v_pk_fma_f32 v[160:161], v[60:61], v[170:171], v[162:163]
	v_pk_fma_f32 v[162:163], v[52:53], v[170:171], v[164:165]
	v_pk_fma_f32 v[164:165], v[50:51], v[170:171], v[166:167]
	v_pk_fma_f32 v[166:167], v[58:59], v[170:171], v[168:169]
	v_lshlrev_b32_e32 v168, 16, v224
	v_pk_fma_f32 v[134:135], v[62:63], v[170:171], v[134:135]
	v_and_b32_e32 v169, 0xffff0000, v224
	v_lshl_add_u64 v[176:177], v[114:115], 0, s[4:5]
	global_load_dword v224, v[176:177], off
	s_waitcnt vmcnt(45)
	v_pk_fma_f32 v[46:47], v[86:87], v[168:169], v[46:47]
	v_pk_fma_f32 v[48:49], v[84:85], v[168:169], v[48:49]
	v_pk_fma_f32 v[136:137], v[82:83], v[168:169], v[136:137]
	v_pk_fma_f32 v[142:143], v[80:81], v[168:169], v[142:143]
	v_pk_fma_f32 v[144:145], v[78:79], v[168:169], v[144:145]
	v_pk_fma_f32 v[146:147], v[76:77], v[168:169], v[146:147]
	v_pk_fma_f32 v[148:149], v[74:75], v[168:169], v[148:149]
	v_pk_fma_f32 v[152:153], v[72:73], v[168:169], v[152:153]
	v_pk_fma_f32 v[154:155], v[70:71], v[168:169], v[154:155]
	v_pk_fma_f32 v[156:157], v[68:69], v[168:169], v[156:157]
	v_pk_fma_f32 v[158:159], v[66:67], v[168:169], v[158:159]
	v_pk_fma_f32 v[134:135], v[64:65], v[168:169], v[134:135]
	v_pk_fma_f32 v[160:161], v[62:63], v[168:169], v[160:161]
	v_pk_fma_f32 v[162:163], v[60:61], v[168:169], v[162:163]
	v_pk_fma_f32 v[164:165], v[52:53], v[168:169], v[164:165]
	v_pk_fma_f32 v[166:167], v[50:51], v[168:169], v[166:167]
	v_lshlrev_b32_e32 v168, 16, v225
	v_and_b32_e32 v169, 0xffff0000, v225
	global_load_dword v225, v[176:177], off offset:2048
	s_add_u32 s4, s4, 0x1000
	s_addc_u32 s5, s5, 0
	s_waitcnt vmcnt(45)
	v_lshlrev_b32_e32 v38, 16, v226
	v_pk_fma_f32 v[42:43], v[88:89], v[168:169], v[46:47]
	v_pk_fma_f32 v[46:47], v[86:87], v[168:169], v[48:49]
	v_pk_fma_f32 v[48:49], v[84:85], v[168:169], v[136:137]
	v_pk_fma_f32 v[136:137], v[82:83], v[168:169], v[142:143]
	v_pk_fma_f32 v[142:143], v[80:81], v[168:169], v[144:145]
	v_pk_fma_f32 v[144:145], v[78:79], v[168:169], v[146:147]
	v_pk_fma_f32 v[146:147], v[76:77], v[168:169], v[148:149]
	v_pk_fma_f32 v[148:149], v[74:75], v[168:169], v[152:153]
	v_pk_fma_f32 v[152:153], v[72:73], v[168:169], v[154:155]
	v_pk_fma_f32 v[154:155], v[70:71], v[168:169], v[156:157]
	v_pk_fma_f32 v[156:157], v[68:69], v[168:169], v[158:159]
	v_pk_fma_f32 v[134:135], v[66:67], v[168:169], v[134:135]
	v_pk_fma_f32 v[158:159], v[64:65], v[168:169], v[160:161]
	v_pk_fma_f32 v[160:161], v[62:63], v[168:169], v[162:163]
	v_pk_fma_f32 v[162:163], v[60:61], v[168:169], v[164:165]
	v_pk_fma_f32 v[164:165], v[52:53], v[168:169], v[166:167]
	v_and_b32_e32 v39, 0xffff0000, v226
	v_lshl_add_u64 v[174:175], v[114:115], 0, s[4:5]
	global_load_dword v226, v[174:175], off
	s_waitcnt vmcnt(45)
	v_pk_fma_f32 v[42:43], v[90:91], v[38:39], v[42:43]
	v_pk_fma_f32 v[46:47], v[88:89], v[38:39], v[46:47]
	v_pk_fma_f32 v[48:49], v[86:87], v[38:39], v[48:49]
	v_pk_fma_f32 v[136:137], v[84:85], v[38:39], v[136:137]
	v_pk_fma_f32 v[142:143], v[82:83], v[38:39], v[142:143]
	v_pk_fma_f32 v[144:145], v[80:81], v[38:39], v[144:145]
	v_pk_fma_f32 v[146:147], v[78:79], v[38:39], v[146:147]
	v_pk_fma_f32 v[148:149], v[76:77], v[38:39], v[148:149]
	v_pk_fma_f32 v[152:153], v[74:75], v[38:39], v[152:153]
	v_pk_fma_f32 v[154:155], v[72:73], v[38:39], v[154:155]
	v_pk_fma_f32 v[156:157], v[70:71], v[38:39], v[156:157]
	v_pk_fma_f32 v[134:135], v[68:69], v[38:39], v[134:135]
	v_pk_fma_f32 v[158:159], v[66:67], v[38:39], v[158:159]
	v_pk_fma_f32 v[160:161], v[64:65], v[38:39], v[160:161]
	v_pk_fma_f32 v[162:163], v[62:63], v[38:39], v[162:163]
	v_pk_fma_f32 v[38:39], v[60:61], v[38:39], v[164:165]
	v_lshlrev_b32_e32 v164, 16, v227
	v_and_b32_e32 v165, 0xffff0000, v227
	global_load_dword v227, v[174:175], off offset:2048
	s_add_u32 s4, s4, 0x1000
	s_addc_u32 s5, s5, 0
	s_waitcnt vmcnt(45)
	v_lshlrev_b32_e32 v32, 16, v228
	v_pk_fma_f32 v[42:43], v[92:93], v[164:165], v[42:43]
	v_pk_fma_f32 v[46:47], v[90:91], v[164:165], v[46:47]
	v_pk_fma_f32 v[48:49], v[88:89], v[164:165], v[48:49]
	v_pk_fma_f32 v[136:137], v[86:87], v[164:165], v[136:137]
	v_pk_fma_f32 v[142:143], v[84:85], v[164:165], v[142:143]
	v_pk_fma_f32 v[144:145], v[82:83], v[164:165], v[144:145]
	v_pk_fma_f32 v[146:147], v[80:81], v[164:165], v[146:147]
	v_pk_fma_f32 v[148:149], v[78:79], v[164:165], v[148:149]
	v_pk_fma_f32 v[152:153], v[76:77], v[164:165], v[152:153]
	v_pk_fma_f32 v[154:155], v[74:75], v[164:165], v[154:155]
	v_pk_fma_f32 v[156:157], v[72:73], v[164:165], v[156:157]
	v_pk_fma_f32 v[134:135], v[70:71], v[164:165], v[134:135]
	v_pk_fma_f32 v[158:159], v[68:69], v[164:165], v[158:159]
	v_pk_fma_f32 v[160:161], v[66:67], v[164:165], v[160:161]
	v_pk_fma_f32 v[162:163], v[64:65], v[164:165], v[162:163]
	v_pk_fma_f32 v[38:39], v[62:63], v[164:165], v[38:39]
	v_and_b32_e32 v33, 0xffff0000, v228
	v_lshl_add_u64 v[176:177], v[114:115], 0, s[4:5]
	global_load_dword v228, v[176:177], off
	s_waitcnt vmcnt(45)
	v_pk_fma_f32 v[42:43], v[94:95], v[32:33], v[42:43]
	v_pk_fma_f32 v[46:47], v[92:93], v[32:33], v[46:47]
	v_pk_fma_f32 v[48:49], v[90:91], v[32:33], v[48:49]
	v_pk_fma_f32 v[136:137], v[88:89], v[32:33], v[136:137]
	v_pk_fma_f32 v[142:143], v[86:87], v[32:33], v[142:143]
	v_pk_fma_f32 v[144:145], v[84:85], v[32:33], v[144:145]
	v_pk_fma_f32 v[146:147], v[82:83], v[32:33], v[146:147]
	v_pk_fma_f32 v[148:149], v[80:81], v[32:33], v[148:149]
	v_pk_fma_f32 v[152:153], v[78:79], v[32:33], v[152:153]
	v_pk_fma_f32 v[154:155], v[76:77], v[32:33], v[154:155]
	v_pk_fma_f32 v[156:157], v[74:75], v[32:33], v[156:157]
	v_pk_fma_f32 v[134:135], v[72:73], v[32:33], v[134:135]
	v_pk_fma_f32 v[158:159], v[70:71], v[32:33], v[158:159]
	v_pk_fma_f32 v[160:161], v[68:69], v[32:33], v[160:161]
	v_pk_fma_f32 v[162:163], v[66:67], v[32:33], v[162:163]
	v_pk_fma_f32 v[32:33], v[64:65], v[32:33], v[38:39]
	v_lshlrev_b32_e32 v38, 16, v229
	v_and_b32_e32 v39, 0xffff0000, v229
	global_load_dword v229, v[176:177], off offset:2048
	s_add_u32 s4, s4, 0x1000
	s_addc_u32 s5, s5, 0
	s_waitcnt vmcnt(45)
	v_pk_fma_f32 v[42:43], v[96:97], v[38:39], v[42:43]
	v_pk_fma_f32 v[46:47], v[94:95], v[38:39], v[46:47]
	v_pk_fma_f32 v[48:49], v[92:93], v[38:39], v[48:49]
	v_pk_fma_f32 v[136:137], v[90:91], v[38:39], v[136:137]
	v_pk_fma_f32 v[142:143], v[88:89], v[38:39], v[142:143]
	v_pk_fma_f32 v[144:145], v[86:87], v[38:39], v[144:145]
	v_pk_fma_f32 v[146:147], v[84:85], v[38:39], v[146:147]
	v_pk_fma_f32 v[148:149], v[82:83], v[38:39], v[148:149]
	v_pk_fma_f32 v[152:153], v[80:81], v[38:39], v[152:153]
	v_pk_fma_f32 v[154:155], v[78:79], v[38:39], v[154:155]
	v_pk_fma_f32 v[156:157], v[76:77], v[38:39], v[156:157]
	v_pk_fma_f32 v[134:135], v[74:75], v[38:39], v[134:135]
	v_pk_fma_f32 v[158:159], v[72:73], v[38:39], v[158:159]
	v_pk_fma_f32 v[160:161], v[70:71], v[38:39], v[160:161]
	v_pk_fma_f32 v[162:163], v[68:69], v[38:39], v[162:163]
	v_pk_fma_f32 v[32:33], v[66:67], v[38:39], v[32:33]
	v_lshlrev_b32_e32 v38, 16, v230
	v_and_b32_e32 v39, 0xffff0000, v230
	v_lshl_add_u64 v[174:175], v[114:115], 0, s[4:5]
	global_load_dword v230, v[174:175], off
	s_waitcnt vmcnt(45)
	v_lshlrev_b32_e32 v36, 16, v231
	v_pk_fma_f32 v[40:41], v[98:99], v[38:39], v[42:43]
	v_pk_fma_f32 v[42:43], v[96:97], v[38:39], v[46:47]
	v_pk_fma_f32 v[46:47], v[94:95], v[38:39], v[48:49]
	v_pk_fma_f32 v[48:49], v[92:93], v[38:39], v[136:137]
	v_pk_fma_f32 v[136:137], v[90:91], v[38:39], v[142:143]
	v_pk_fma_f32 v[142:143], v[88:89], v[38:39], v[144:145]
	v_pk_fma_f32 v[144:145], v[86:87], v[38:39], v[146:147]
	v_pk_fma_f32 v[146:147], v[84:85], v[38:39], v[148:149]
	v_pk_fma_f32 v[148:149], v[82:83], v[38:39], v[152:153]
	v_pk_fma_f32 v[152:153], v[80:81], v[38:39], v[154:155]
	v_pk_fma_f32 v[154:155], v[78:79], v[38:39], v[156:157]
	v_pk_fma_f32 v[134:135], v[76:77], v[38:39], v[134:135]
	v_pk_fma_f32 v[156:157], v[74:75], v[38:39], v[158:159]
	v_pk_fma_f32 v[158:159], v[72:73], v[38:39], v[160:161]
	v_pk_fma_f32 v[160:161], v[70:71], v[38:39], v[162:163]
	v_pk_fma_f32 v[32:33], v[68:69], v[38:39], v[32:33]
	v_and_b32_e32 v37, 0xffff0000, v231
	global_load_dword v231, v[174:175], off offset:2048
	s_add_u32 s4, s4, 0x1000
	s_addc_u32 s5, s5, 0
	s_waitcnt vmcnt(45)
	v_pk_fma_f32 v[38:39], v[100:101], v[36:37], v[40:41]
	v_pk_fma_f32 v[40:41], v[98:99], v[36:37], v[42:43]
	v_pk_fma_f32 v[42:43], v[96:97], v[36:37], v[46:47]
	v_pk_fma_f32 v[46:47], v[94:95], v[36:37], v[48:49]
	v_pk_fma_f32 v[48:49], v[92:93], v[36:37], v[136:137]
	v_pk_fma_f32 v[136:137], v[90:91], v[36:37], v[142:143]
	v_pk_fma_f32 v[142:143], v[88:89], v[36:37], v[144:145]
	v_pk_fma_f32 v[144:145], v[86:87], v[36:37], v[146:147]
	v_pk_fma_f32 v[146:147], v[84:85], v[36:37], v[148:149]
	v_pk_fma_f32 v[148:149], v[82:83], v[36:37], v[152:153]
	v_pk_fma_f32 v[152:153], v[80:81], v[36:37], v[154:155]
	v_pk_fma_f32 v[134:135], v[78:79], v[36:37], v[134:135]
	v_pk_fma_f32 v[154:155], v[76:77], v[36:37], v[156:157]
	v_pk_fma_f32 v[156:157], v[74:75], v[36:37], v[158:159]
	v_pk_fma_f32 v[158:159], v[72:73], v[36:37], v[160:161]
	v_pk_fma_f32 v[32:33], v[70:71], v[36:37], v[32:33]
	v_lshlrev_b32_e32 v36, 16, v232
	v_and_b32_e32 v37, 0xffff0000, v232
	v_lshl_add_u64 v[176:177], v[114:115], 0, s[4:5]
	global_load_dword v232, v[176:177], off
	s_waitcnt vmcnt(45)
	v_pk_fma_f32 v[38:39], v[102:103], v[36:37], v[38:39]
	v_pk_fma_f32 v[40:41], v[100:101], v[36:37], v[40:41]
	v_pk_fma_f32 v[42:43], v[98:99], v[36:37], v[42:43]
	v_pk_fma_f32 v[46:47], v[96:97], v[36:37], v[46:47]
	v_pk_fma_f32 v[48:49], v[94:95], v[36:37], v[48:49]
	v_pk_fma_f32 v[136:137], v[92:93], v[36:37], v[136:137]
	v_pk_fma_f32 v[142:143], v[90:91], v[36:37], v[142:143]
	v_pk_fma_f32 v[144:145], v[88:89], v[36:37], v[144:145]
	v_pk_fma_f32 v[146:147], v[86:87], v[36:37], v[146:147]
	v_pk_fma_f32 v[148:149], v[84:85], v[36:37], v[148:149]
	v_pk_fma_f32 v[152:153], v[82:83], v[36:37], v[152:153]
	v_pk_fma_f32 v[134:135], v[80:81], v[36:37], v[134:135]
	v_pk_fma_f32 v[154:155], v[78:79], v[36:37], v[154:155]
	v_pk_fma_f32 v[156:157], v[76:77], v[36:37], v[156:157]
	v_pk_fma_f32 v[158:159], v[74:75], v[36:37], v[158:159]
	v_pk_fma_f32 v[32:33], v[72:73], v[36:37], v[32:33]
	v_lshlrev_b32_e32 v36, 16, v233
	v_and_b32_e32 v37, 0xffff0000, v233
	global_load_dword v233, v[176:177], off offset:2048
	s_add_u32 s4, s4, 0x1000
	s_addc_u32 s5, s5, 0
	s_waitcnt vmcnt(45)
	v_pk_fma_f32 v[38:39], v[104:105], v[36:37], v[38:39]
	v_pk_fma_f32 v[40:41], v[102:103], v[36:37], v[40:41]
	v_pk_fma_f32 v[42:43], v[100:101], v[36:37], v[42:43]
	v_pk_fma_f32 v[46:47], v[98:99], v[36:37], v[46:47]
	v_pk_fma_f32 v[48:49], v[96:97], v[36:37], v[48:49]
	v_pk_fma_f32 v[136:137], v[94:95], v[36:37], v[136:137]
	v_pk_fma_f32 v[142:143], v[92:93], v[36:37], v[142:143]
	v_pk_fma_f32 v[144:145], v[90:91], v[36:37], v[144:145]
	v_pk_fma_f32 v[146:147], v[88:89], v[36:37], v[146:147]
	v_pk_fma_f32 v[148:149], v[86:87], v[36:37], v[148:149]
	v_pk_fma_f32 v[152:153], v[84:85], v[36:37], v[152:153]
	v_pk_fma_f32 v[134:135], v[82:83], v[36:37], v[134:135]
	v_pk_fma_f32 v[154:155], v[80:81], v[36:37], v[154:155]
	v_pk_fma_f32 v[156:157], v[78:79], v[36:37], v[156:157]
	v_pk_fma_f32 v[158:159], v[76:77], v[36:37], v[158:159]
	v_pk_fma_f32 v[32:33], v[74:75], v[36:37], v[32:33]
	v_lshlrev_b32_e32 v36, 16, v234
	v_and_b32_e32 v37, 0xffff0000, v234
	v_lshl_add_u64 v[174:175], v[114:115], 0, s[4:5]
	global_load_dword v234, v[174:175], off
	s_waitcnt vmcnt(45)
	v_pk_fma_f32 v[38:39], v[106:107], v[36:37], v[38:39]
	v_pk_fma_f32 v[40:41], v[104:105], v[36:37], v[40:41]
	v_pk_fma_f32 v[42:43], v[102:103], v[36:37], v[42:43]
	v_pk_fma_f32 v[46:47], v[100:101], v[36:37], v[46:47]
	v_pk_fma_f32 v[48:49], v[98:99], v[36:37], v[48:49]
	v_pk_fma_f32 v[136:137], v[96:97], v[36:37], v[136:137]
	v_pk_fma_f32 v[142:143], v[94:95], v[36:37], v[142:143]
	v_pk_fma_f32 v[144:145], v[92:93], v[36:37], v[144:145]
	v_pk_fma_f32 v[146:147], v[90:91], v[36:37], v[146:147]
	v_pk_fma_f32 v[148:149], v[88:89], v[36:37], v[148:149]
	v_pk_fma_f32 v[152:153], v[86:87], v[36:37], v[152:153]
	v_pk_fma_f32 v[134:135], v[84:85], v[36:37], v[134:135]
	v_pk_fma_f32 v[154:155], v[82:83], v[36:37], v[154:155]
	v_pk_fma_f32 v[156:157], v[80:81], v[36:37], v[156:157]
	v_pk_fma_f32 v[158:159], v[78:79], v[36:37], v[158:159]
	v_pk_fma_f32 v[32:33], v[76:77], v[36:37], v[32:33]
	v_lshlrev_b32_e32 v36, 16, v235
	v_and_b32_e32 v37, 0xffff0000, v235
	global_load_dword v235, v[174:175], off offset:2048
	s_add_u32 s4, s4, 0x1000
	s_addc_u32 s5, s5, 0
	s_waitcnt vmcnt(45)
	v_lshlrev_b32_e32 v18, 16, v236
	v_pk_fma_f32 v[20:21], v[108:109], v[36:37], v[38:39]
	v_pk_fma_f32 v[38:39], v[106:107], v[36:37], v[40:41]
	v_pk_fma_f32 v[40:41], v[104:105], v[36:37], v[42:43]
	v_pk_fma_f32 v[42:43], v[102:103], v[36:37], v[46:47]
	v_pk_fma_f32 v[46:47], v[100:101], v[36:37], v[48:49]
	v_pk_fma_f32 v[48:49], v[98:99], v[36:37], v[136:137]
	v_pk_fma_f32 v[136:137], v[96:97], v[36:37], v[142:143]
	v_pk_fma_f32 v[142:143], v[94:95], v[36:37], v[144:145]
	v_pk_fma_f32 v[144:145], v[92:93], v[36:37], v[146:147]
	v_pk_fma_f32 v[146:147], v[90:91], v[36:37], v[148:149]
	v_pk_fma_f32 v[148:149], v[88:89], v[36:37], v[152:153]
	v_pk_fma_f32 v[134:135], v[86:87], v[36:37], v[134:135]
	v_pk_fma_f32 v[152:153], v[84:85], v[36:37], v[154:155]
	v_pk_fma_f32 v[154:155], v[82:83], v[36:37], v[156:157]
	v_pk_fma_f32 v[156:157], v[80:81], v[36:37], v[158:159]
	v_pk_fma_f32 v[32:33], v[78:79], v[36:37], v[32:33]
	v_and_b32_e32 v19, 0xffff0000, v236
	v_lshl_add_u64 v[176:177], v[114:115], 0, s[4:5]
	global_load_dword v236, v[176:177], off
	s_waitcnt vmcnt(45)
	v_pk_fma_f32 v[20:21], v[110:111], v[18:19], v[20:21]
	v_pk_fma_f32 v[36:37], v[108:109], v[18:19], v[38:39]
	v_pk_fma_f32 v[38:39], v[106:107], v[18:19], v[40:41]
	v_pk_fma_f32 v[40:41], v[104:105], v[18:19], v[42:43]
	v_pk_fma_f32 v[42:43], v[102:103], v[18:19], v[46:47]
	v_pk_fma_f32 v[46:47], v[100:101], v[18:19], v[48:49]
	v_pk_fma_f32 v[48:49], v[98:99], v[18:19], v[136:137]
	v_pk_fma_f32 v[136:137], v[96:97], v[18:19], v[142:143]
	v_pk_fma_f32 v[142:143], v[94:95], v[18:19], v[144:145]
	v_pk_fma_f32 v[144:145], v[92:93], v[18:19], v[146:147]
	v_pk_fma_f32 v[146:147], v[90:91], v[18:19], v[148:149]
	v_pk_fma_f32 v[134:135], v[88:89], v[18:19], v[134:135]
	v_pk_fma_f32 v[148:149], v[86:87], v[18:19], v[152:153]
	v_pk_fma_f32 v[152:153], v[84:85], v[18:19], v[154:155]
	v_pk_fma_f32 v[154:155], v[82:83], v[18:19], v[156:157]
	v_pk_fma_f32 v[18:19], v[80:81], v[18:19], v[32:33]
	v_lshlrev_b32_e32 v32, 16, v237
	v_and_b32_e32 v33, 0xffff0000, v237
	global_load_dword v237, v[176:177], off offset:2048
	s_add_u32 s4, s4, 0x1000
	s_addc_u32 s5, s5, 0
	s_waitcnt vmcnt(45)
	v_lshlrev_b32_e32 v30, 16, v238
	v_pk_fma_f32 v[38:39], v[108:109], v[32:33], v[38:39]
	v_pk_fma_f32 v[40:41], v[106:107], v[32:33], v[40:41]
	v_pk_fma_f32 v[42:43], v[104:105], v[32:33], v[42:43]
	v_pk_fma_f32 v[46:47], v[102:103], v[32:33], v[46:47]
	v_pk_fma_f32 v[48:49], v[100:101], v[32:33], v[48:49]
	v_pk_fma_f32 v[136:137], v[98:99], v[32:33], v[136:137]
	v_pk_fma_f32 v[142:143], v[96:97], v[32:33], v[142:143]
	v_pk_fma_f32 v[144:145], v[94:95], v[32:33], v[144:145]
	v_pk_fma_f32 v[146:147], v[92:93], v[32:33], v[146:147]
	v_pk_fma_f32 v[134:135], v[90:91], v[32:33], v[134:135]
	v_pk_fma_f32 v[148:149], v[88:89], v[32:33], v[148:149]
	v_pk_fma_f32 v[152:153], v[86:87], v[32:33], v[152:153]
	v_pk_fma_f32 v[154:155], v[84:85], v[32:33], v[154:155]
	v_pk_fma_f32 v[18:19], v[82:83], v[32:33], v[18:19]
	v_and_b32_e32 v31, 0xffff0000, v238
	v_lshl_add_u64 v[174:175], v[114:115], 0, s[4:5]
	global_load_dword v238, v[174:175], off
	s_waitcnt vmcnt(45)
	v_pk_fma_f32 v[36:37], v[110:111], v[32:33], v[36:37]
	v_pk_fma_f32 v[32:33], v[110:111], v[30:31], v[38:39]
	v_pk_fma_f32 v[38:39], v[108:109], v[30:31], v[40:41]
	v_pk_fma_f32 v[40:41], v[106:107], v[30:31], v[42:43]
	v_pk_fma_f32 v[42:43], v[104:105], v[30:31], v[46:47]
	v_pk_fma_f32 v[46:47], v[102:103], v[30:31], v[48:49]
	v_pk_fma_f32 v[48:49], v[100:101], v[30:31], v[136:137]
	v_pk_fma_f32 v[136:137], v[98:99], v[30:31], v[142:143]
	v_pk_fma_f32 v[142:143], v[96:97], v[30:31], v[144:145]
	v_pk_fma_f32 v[144:145], v[94:95], v[30:31], v[146:147]
	v_pk_fma_f32 v[134:135], v[92:93], v[30:31], v[134:135]
	v_pk_fma_f32 v[146:147], v[90:91], v[30:31], v[148:149]
	v_pk_fma_f32 v[148:149], v[88:89], v[30:31], v[152:153]
	v_pk_fma_f32 v[152:153], v[86:87], v[30:31], v[154:155]
	v_pk_fma_f32 v[18:19], v[84:85], v[30:31], v[18:19]
	v_lshlrev_b32_e32 v30, 16, v239
	v_and_b32_e32 v31, 0xffff0000, v239
	global_load_dword v239, v[174:175], off offset:2048
	s_add_u32 s4, s4, 0x1000
	s_addc_u32 s5, s5, 0
	s_waitcnt vmcnt(45)
	v_lshlrev_b32_e32 v22, 16, v240
	v_pk_fma_f32 v[40:41], v[108:109], v[30:31], v[40:41]
	v_pk_fma_f32 v[42:43], v[106:107], v[30:31], v[42:43]
	v_pk_fma_f32 v[46:47], v[104:105], v[30:31], v[46:47]
	v_pk_fma_f32 v[48:49], v[102:103], v[30:31], v[48:49]
	v_pk_fma_f32 v[136:137], v[100:101], v[30:31], v[136:137]
	v_pk_fma_f32 v[142:143], v[98:99], v[30:31], v[142:143]
	v_pk_fma_f32 v[144:145], v[96:97], v[30:31], v[144:145]
	v_pk_fma_f32 v[134:135], v[94:95], v[30:31], v[134:135]
	v_pk_fma_f32 v[146:147], v[92:93], v[30:31], v[146:147]
	v_pk_fma_f32 v[148:149], v[90:91], v[30:31], v[148:149]
	v_pk_fma_f32 v[152:153], v[88:89], v[30:31], v[152:153]
	v_pk_fma_f32 v[18:19], v[86:87], v[30:31], v[18:19]
	v_and_b32_e32 v23, 0xffff0000, v240
	v_lshl_add_u64 v[176:177], v[114:115], 0, s[4:5]
	global_load_dword v240, v[176:177], off
	s_waitcnt vmcnt(45)
	v_pk_fma_f32 v[38:39], v[110:111], v[30:31], v[38:39]
	v_pk_fma_f32 v[30:31], v[110:111], v[22:23], v[40:41]
	v_pk_fma_f32 v[40:41], v[108:109], v[22:23], v[42:43]
	v_pk_fma_f32 v[42:43], v[106:107], v[22:23], v[46:47]
	v_pk_fma_f32 v[46:47], v[104:105], v[22:23], v[48:49]
	v_pk_fma_f32 v[48:49], v[102:103], v[22:23], v[136:137]
	v_pk_fma_f32 v[136:137], v[100:101], v[22:23], v[142:143]
	v_pk_fma_f32 v[142:143], v[98:99], v[22:23], v[144:145]
	v_pk_fma_f32 v[134:135], v[96:97], v[22:23], v[134:135]
	v_pk_fma_f32 v[144:145], v[94:95], v[22:23], v[146:147]
	v_pk_fma_f32 v[146:147], v[92:93], v[22:23], v[148:149]
	v_pk_fma_f32 v[148:149], v[90:91], v[22:23], v[152:153]
	v_pk_fma_f32 v[18:19], v[88:89], v[22:23], v[18:19]
	v_lshlrev_b32_e32 v22, 16, v241
	v_and_b32_e32 v23, 0xffff0000, v241
	global_load_dword v241, v[176:177], off offset:2048
	s_add_u32 s4, s4, 0x1000
	s_addc_u32 s5, s5, 0
	s_waitcnt vmcnt(45)
	v_pk_fma_f32 v[24:25], v[110:111], v[22:23], v[40:41]
	v_pk_fma_f32 v[40:41], v[108:109], v[22:23], v[42:43]
	v_pk_fma_f32 v[42:43], v[106:107], v[22:23], v[46:47]
	v_pk_fma_f32 v[46:47], v[104:105], v[22:23], v[48:49]
	v_pk_fma_f32 v[48:49], v[102:103], v[22:23], v[136:137]
	v_pk_fma_f32 v[136:137], v[100:101], v[22:23], v[142:143]
	v_pk_fma_f32 v[134:135], v[98:99], v[22:23], v[134:135]
	v_pk_fma_f32 v[142:143], v[96:97], v[22:23], v[144:145]
	v_pk_fma_f32 v[144:145], v[94:95], v[22:23], v[146:147]
	v_pk_fma_f32 v[146:147], v[92:93], v[22:23], v[148:149]
	v_pk_fma_f32 v[18:19], v[90:91], v[22:23], v[18:19]
	v_lshlrev_b32_e32 v22, 16, v242
	v_and_b32_e32 v23, 0xffff0000, v242
	v_lshl_add_u64 v[174:175], v[114:115], 0, s[4:5]
	global_load_dword v242, v[174:175], off
	s_waitcnt vmcnt(45)
	v_pk_fma_f32 v[26:27], v[110:111], v[22:23], v[40:41]
	v_pk_fma_f32 v[40:41], v[108:109], v[22:23], v[42:43]
	v_pk_fma_f32 v[42:43], v[106:107], v[22:23], v[46:47]
	v_pk_fma_f32 v[46:47], v[104:105], v[22:23], v[48:49]
	v_pk_fma_f32 v[48:49], v[102:103], v[22:23], v[136:137]
	v_pk_fma_f32 v[134:135], v[100:101], v[22:23], v[134:135]
	v_pk_fma_f32 v[136:137], v[98:99], v[22:23], v[142:143]
	v_pk_fma_f32 v[142:143], v[96:97], v[22:23], v[144:145]
	v_pk_fma_f32 v[144:145], v[94:95], v[22:23], v[146:147]
	v_pk_fma_f32 v[18:19], v[92:93], v[22:23], v[18:19]
	v_lshlrev_b32_e32 v22, 16, v243
	v_and_b32_e32 v23, 0xffff0000, v243
	global_load_dword v243, v[174:175], off offset:2048
	s_add_u32 s4, s4, 0x1000
	s_addc_u32 s5, s5, 0
	s_waitcnt vmcnt(45)
	v_pk_fma_f32 v[28:29], v[110:111], v[22:23], v[40:41]
	v_pk_fma_f32 v[40:41], v[108:109], v[22:23], v[42:43]
	v_pk_fma_f32 v[42:43], v[106:107], v[22:23], v[46:47]
	v_pk_fma_f32 v[46:47], v[104:105], v[22:23], v[48:49]
	v_pk_fma_f32 v[48:49], v[102:103], v[22:23], v[134:135]
	v_pk_fma_f32 v[134:135], v[100:101], v[22:23], v[136:137]
	v_pk_fma_f32 v[136:137], v[98:99], v[22:23], v[142:143]
	v_pk_fma_f32 v[142:143], v[96:97], v[22:23], v[144:145]
	v_pk_fma_f32 v[18:19], v[94:95], v[22:23], v[18:19]
	v_lshlrev_b32_e32 v22, 16, v244
	v_and_b32_e32 v23, 0xffff0000, v244
	v_lshl_add_u64 v[176:177], v[114:115], 0, s[4:5]
	global_load_dword v244, v[176:177], off
	s_waitcnt vmcnt(45)
	v_pk_fma_f32 v[34:35], v[110:111], v[22:23], v[40:41]
	v_pk_fma_f32 v[40:41], v[108:109], v[22:23], v[42:43]
	v_pk_fma_f32 v[42:43], v[106:107], v[22:23], v[46:47]
	v_pk_fma_f32 v[46:47], v[104:105], v[22:23], v[48:49]
	v_pk_fma_f32 v[48:49], v[102:103], v[22:23], v[134:135]
	v_pk_fma_f32 v[134:135], v[100:101], v[22:23], v[136:137]
	v_pk_fma_f32 v[136:137], v[98:99], v[22:23], v[142:143]
	v_pk_fma_f32 v[18:19], v[96:97], v[22:23], v[18:19]
	v_lshlrev_b32_e32 v22, 16, v245
	v_and_b32_e32 v23, 0xffff0000, v245
	global_load_dword v245, v[176:177], off offset:2048
	s_add_u32 s4, s4, 0x1000
	s_addc_u32 s5, s5, 0
	s_waitcnt vmcnt(45)
	v_pk_fma_f32 v[40:41], v[110:111], v[22:23], v[40:41]
	v_pk_fma_f32 v[42:43], v[108:109], v[22:23], v[42:43]
	v_pk_fma_f32 v[44:45], v[106:107], v[22:23], v[46:47]
	v_pk_fma_f32 v[46:47], v[104:105], v[22:23], v[48:49]
	v_pk_fma_f32 v[48:49], v[102:103], v[22:23], v[134:135]
	v_pk_fma_f32 v[134:135], v[100:101], v[22:23], v[136:137]
	v_pk_fma_f32 v[18:19], v[98:99], v[22:23], v[18:19]
	v_lshlrev_b32_e32 v22, 16, v246
	v_and_b32_e32 v23, 0xffff0000, v246
	v_lshl_add_u64 v[174:175], v[114:115], 0, s[4:5]
	global_load_dword v246, v[174:175], off
	s_waitcnt vmcnt(45)
	v_pk_fma_f32 v[42:43], v[110:111], v[22:23], v[42:43]
	v_pk_fma_f32 v[44:45], v[108:109], v[22:23], v[44:45]
	v_pk_fma_f32 v[46:47], v[106:107], v[22:23], v[46:47]
	v_pk_fma_f32 v[48:49], v[104:105], v[22:23], v[48:49]
	v_pk_fma_f32 v[118:119], v[102:103], v[22:23], v[134:135]
	v_pk_fma_f32 v[18:19], v[100:101], v[22:23], v[18:19]
	v_lshlrev_b32_e32 v22, 16, v247
	v_and_b32_e32 v23, 0xffff0000, v247
	global_load_dword v247, v[174:175], off offset:2048
	s_add_u32 s4, s4, 0x1000
	s_addc_u32 s5, s5, 0
	s_waitcnt vmcnt(45)
	v_pk_fma_f32 v[44:45], v[110:111], v[22:23], v[44:45]
	v_pk_fma_f32 v[46:47], v[108:109], v[22:23], v[46:47]
	v_pk_fma_f32 v[48:49], v[106:107], v[22:23], v[48:49]
	v_pk_fma_f32 v[118:119], v[104:105], v[22:23], v[118:119]
	v_pk_fma_f32 v[18:19], v[102:103], v[22:23], v[18:19]
	v_lshlrev_b32_e32 v22, 16, v248
	v_and_b32_e32 v23, 0xffff0000, v248
	v_lshl_add_u64 v[176:177], v[114:115], 0, s[4:5]
	global_load_dword v248, v[176:177], off
	s_waitcnt vmcnt(45)
	v_pk_fma_f32 v[46:47], v[110:111], v[22:23], v[46:47]
	v_pk_fma_f32 v[48:49], v[108:109], v[22:23], v[48:49]
	v_pk_fma_f32 v[118:119], v[106:107], v[22:23], v[118:119]
	v_pk_fma_f32 v[18:19], v[104:105], v[22:23], v[18:19]
	v_lshlrev_b32_e32 v22, 16, v249
	v_and_b32_e32 v23, 0xffff0000, v249
	global_load_dword v249, v[176:177], off offset:2048
	s_add_u32 s4, s4, 0x1000
	s_addc_u32 s5, s5, 0
	s_waitcnt vmcnt(45)
	v_pk_fma_f32 v[48:49], v[110:111], v[22:23], v[48:49]
	v_pk_fma_f32 v[118:119], v[108:109], v[22:23], v[118:119]
	v_pk_fma_f32 v[18:19], v[106:107], v[22:23], v[18:19]
	v_lshlrev_b32_e32 v22, 16, v250
	v_and_b32_e32 v23, 0xffff0000, v250
	v_lshl_add_u64 v[174:175], v[114:115], 0, s[4:5]
	global_load_dword v250, v[174:175], off
	s_waitcnt vmcnt(45)
	v_pk_fma_f32 v[118:119], v[110:111], v[22:23], v[118:119]
	v_pk_fma_f32 v[18:19], v[108:109], v[22:23], v[18:19]
	v_lshlrev_b32_e32 v22, 16, v251
	v_and_b32_e32 v23, 0xffff0000, v251
	global_load_dword v251, v[174:175], off offset:2048
	s_add_u32 s4, s4, 0x1000
	s_addc_u32 s5, s5, 0
	v_pk_fma_f32 v[18:19], v[110:111], v[22:23], v[18:19]
	s_branch .Ldw_tail
